# s5_gen step 4 on f32 matrix cores (v_mfma_f32_16x16x4_f32) with a padded LDS copy of C; transposes re-split 4/12/8 tiles over the three WG groups
# speedup vs baseline: 1.0978x; 1.0036x over previous
.LBB0_52:
	v_writelane_b32 v253, s24, 58
	s_nop 1
	v_writelane_b32 v253, s25, 59
	s_or_b64 exec, exec, s[8:9]
	s_load_dwordx16 s[4:19], s[0:1], 0x80
	s_load_dwordx16 s[56:71], s[0:1], 0x138
	s_waitcnt lgkmcnt(0)
	v_writelane_b32 v253, s4, 60
	s_nop 1
	v_writelane_b32 v254, s8, 0
	v_writelane_b32 v254, s9, 1
	v_writelane_b32 v254, s10, 2
	v_writelane_b32 v254, s11, 3
	v_writelane_b32 v254, s12, 4
	v_writelane_b32 v254, s13, 5
	v_writelane_b32 v254, s14, 6
	v_writelane_b32 v254, s15, 7
	v_writelane_b32 v254, s16, 8
	v_writelane_b32 v253, s5, 61
	v_writelane_b32 v254, s17, 9
	v_writelane_b32 v253, s6, 62
	v_writelane_b32 v254, s18, 10
	v_writelane_b32 v253, s7, 63
	v_writelane_b32 v254, s19, 11
	s_load_dwordx16 s[4:19], s[0:1], 0xc0
	v_readlane_b32 s24, v253, 18
	v_readlane_b32 s25, v253, 19
	v_readlane_b32 s26, v253, 20
	v_readlane_b32 s27, v253, 21
	s_waitcnt lgkmcnt(0)
	v_writelane_b32 v254, s4, 12
	v_readlane_b32 s28, v253, 22
	v_readlane_b32 s29, v253, 23
	v_writelane_b32 v254, s5, 13
	v_writelane_b32 v254, s6, 14
	v_writelane_b32 v254, s7, 15
	v_writelane_b32 v254, s8, 16
	v_writelane_b32 v254, s9, 17
	v_writelane_b32 v254, s10, 18
	v_writelane_b32 v254, s11, 19
	v_writelane_b32 v254, s12, 20
	v_writelane_b32 v254, s13, 21
	v_writelane_b32 v254, s14, 22
	v_writelane_b32 v254, s15, 23
	v_writelane_b32 v254, s16, 24
	v_writelane_b32 v254, s17, 25
	v_writelane_b32 v254, s18, 26
	v_writelane_b32 v254, s19, 27
	s_mov_b64 s[4:5], s[76:77]
	s_mov_b64 s[12:13], s[84:85]
	s_mov_b64 s[6:7], s[78:79]
	s_mov_b64 s[14:15], s[86:87]
	s_mov_b64 s[10:11], s[82:83]
	s_mov_b64 s[18:19], s[90:91]
	v_readlane_b32 s30, v253, 24
	v_readlane_b32 s31, v253, 25
	v_writelane_b32 v253, s4, 42
	v_readfirstlane_b32 s0, v234
	s_lshr_b32 s0, s0, 8
	v_writelane_b32 v253, s5, 43
	v_writelane_b32 v253, s6, 44
	v_writelane_b32 v253, s7, 45
	v_writelane_b32 v253, s8, 46
	v_writelane_b32 v253, s9, 47
	v_writelane_b32 v253, s10, 48
	v_writelane_b32 v253, s11, 49
	v_writelane_b32 v253, s12, 50
	v_writelane_b32 v253, s13, 51
	v_writelane_b32 v253, s14, 52
	v_writelane_b32 v253, s15, 53
	v_writelane_b32 v253, s16, 54
	v_writelane_b32 v253, s17, 55
	s_add_i32 s40, s0, s92
	s_lshl_b32 s93, s30, 1
	v_writelane_b32 v253, s18, 56
	v_writelane_b32 v253, s19, 57
	s_movk_i32 s98, 0xc0
	s_cmpk_lt_u32 s40, 0xc0
	s_cbranch_scc1 .Ltr_go
	s_cmpk_gt_u32 s40, 0xff
	s_cbranch_scc1 .Ltr_goC
	s_add_i32 s40, s40, 0x240
	s_movk_i32 s98, 0x40
	s_branch .Ltr_goB
.Ltr_goC:
	s_add_i32 s40, s40, 0x500
	s_movk_i32 s98, 0x100
	s_branch .Ltr_goC2

.Ltp_nz_5:
	ds_write_b32 v22, v32
	ds_write_b32 v22, v33 offset:1040
	ds_write_b32 v22, v34 offset:2080
	ds_write_b32 v22, v35 offset:3120
	ds_write_b32 v22, v36 offset:4160
	ds_write_b32 v22, v37 offset:5200
	ds_write_b32 v22, v38 offset:6240
	ds_write_b32 v22, v39 offset:7280
	ds_write_b32 v22, v40 offset:8320
	ds_write_b32 v22, v41 offset:9360
	ds_write_b32 v22, v42 offset:10400
	ds_write_b32 v22, v43 offset:11440
	ds_write_b32 v22, v44 offset:12480
	ds_write_b32 v22, v45 offset:13520
	ds_write_b32 v22, v46 offset:14560
	ds_write_b32 v22, v47 offset:15600
	v_mov_b32_e32 v3, s77
	v_mad_u32_u24 v2, v112, v3, v113
	s_mov_b64 s[94:95], s[78:79]
	s_waitcnt lgkmcnt(0)
	s_barrier
	ds_read2_b32 v[4:5], v24 offset1:65
	ds_read2_b32 v[6:7], v24 offset0:130 offset1:195
	ds_read2_b32 v[8:9], v25 offset0:4 offset1:69
	ds_read2_b32 v[10:11], v25 offset0:134 offset1:199
	ds_read2_b32 v[12:13], v26 offset0:8 offset1:73
	ds_read2_b32 v[14:15], v26 offset0:138 offset1:203
	ds_read2_b32 v[16:17], v27 offset0:12 offset1:77
	ds_read2_b32 v[18:19], v27 offset0:142 offset1:207
	s_waitcnt lgkmcnt(4)
	v_cvt_pk_bf16_f32 v4, v4, v5
	v_cvt_pk_bf16_f32 v5, v6, v7
	v_cvt_pk_bf16_f32 v6, v8, v9
	v_cvt_pk_bf16_f32 v7, v10, v11
	global_store_dwordx4 v2, v[4:7], s[94:95]
	s_waitcnt lgkmcnt(0)
	v_cvt_pk_bf16_f32 v8, v12, v13
	v_cvt_pk_bf16_f32 v9, v14, v15
	v_cvt_pk_bf16_f32 v10, v16, v17
	v_cvt_pk_bf16_f32 v11, v18, v19
	global_store_dwordx4 v2, v[8:11], s[94:95] offset:16
	s_waitcnt vmcnt(34)
	s_cmpk_ge_i32 s80, 0x40
	s_cbranch_scc1 .Ltp_nz_6
	v_cmp_gt_i32_e32 vcc, s80, v20
	v_cndmask_b32_e32 v48, 0, v48, vcc
	v_cndmask_b32_e32 v49, 0, v49, vcc
	v_cndmask_b32_e32 v50, 0, v50, vcc
	v_cndmask_b32_e32 v51, 0, v51, vcc
	v_cndmask_b32_e32 v52, 0, v52, vcc
	v_cndmask_b32_e32 v53, 0, v53, vcc
	v_cndmask_b32_e32 v54, 0, v54, vcc
	v_cndmask_b32_e32 v55, 0, v55, vcc
	v_cndmask_b32_e32 v56, 0, v56, vcc
	v_cndmask_b32_e32 v57, 0, v57, vcc
	v_cndmask_b32_e32 v58, 0, v58, vcc
	v_cndmask_b32_e32 v59, 0, v59, vcc
	v_cndmask_b32_e32 v60, 0, v60, vcc
	v_cndmask_b32_e32 v61, 0, v61, vcc
	v_cndmask_b32_e32 v62, 0, v62, vcc
	v_cndmask_b32_e32 v63, 0, v63, vcc
.Ltp_nz_6:
	ds_write_b32 v23, v48
	ds_write_b32 v23, v49 offset:1040
	ds_write_b32 v23, v50 offset:2080
	ds_write_b32 v23, v51 offset:3120
	ds_write_b32 v23, v52 offset:4160
	ds_write_b32 v23, v53 offset:5200
	ds_write_b32 v23, v54 offset:6240
	ds_write_b32 v23, v55 offset:7280
	ds_write_b32 v23, v56 offset:8320
	ds_write_b32 v23, v57 offset:9360
	ds_write_b32 v23, v58 offset:10400
	ds_write_b32 v23, v59 offset:11440
	ds_write_b32 v23, v60 offset:12480
	ds_write_b32 v23, v61 offset:13520
	ds_write_b32 v23, v62 offset:14560
	ds_write_b32 v23, v63 offset:15600
	v_mov_b32_e32 v3, s81
	v_mad_u32_u24 v2, v112, v3, v113
	s_mov_b64 s[94:95], s[82:83]
	s_waitcnt lgkmcnt(0)
	s_barrier
	ds_read2_b32 v[4:5], v28 offset1:65
	ds_read2_b32 v[6:7], v28 offset0:130 offset1:195
	ds_read2_b32 v[8:9], v29 offset0:4 offset1:69
	ds_read2_b32 v[10:11], v29 offset0:134 offset1:199
	ds_read2_b32 v[12:13], v30 offset0:8 offset1:73
	ds_read2_b32 v[14:15], v30 offset0:138 offset1:203
	ds_read2_b32 v[16:17], v31 offset0:12 offset1:77
	ds_read2_b32 v[18:19], v31 offset0:142 offset1:207
	s_waitcnt lgkmcnt(4)
	v_cvt_pk_bf16_f32 v4, v4, v5
	v_cvt_pk_bf16_f32 v5, v6, v7
	v_cvt_pk_bf16_f32 v6, v8, v9
	v_cvt_pk_bf16_f32 v7, v10, v11
	global_store_dwordx4 v2, v[4:7], s[94:95]
	s_waitcnt lgkmcnt(0)
	v_cvt_pk_bf16_f32 v8, v12, v13
	v_cvt_pk_bf16_f32 v9, v14, v15
	v_cvt_pk_bf16_f32 v10, v16, v17
	v_cvt_pk_bf16_f32 v11, v18, v19
	global_store_dwordx4 v2, v[8:11], s[94:95] offset:16
	s_waitcnt vmcnt(20)
	s_cmpk_ge_i32 s84, 0x40
	s_cbranch_scc1 .Ltp_nz_7
	v_cmp_gt_i32_e32 vcc, s84, v20
	v_cndmask_b32_e32 v64, 0, v64, vcc
	v_cndmask_b32_e32 v65, 0, v65, vcc
	v_cndmask_b32_e32 v66, 0, v66, vcc
	v_cndmask_b32_e32 v67, 0, v67, vcc
	v_cndmask_b32_e32 v68, 0, v68, vcc
	v_cndmask_b32_e32 v69, 0, v69, vcc
	v_cndmask_b32_e32 v70, 0, v70, vcc
	v_cndmask_b32_e32 v71, 0, v71, vcc
	v_cndmask_b32_e32 v72, 0, v72, vcc
	v_cndmask_b32_e32 v73, 0, v73, vcc
	v_cndmask_b32_e32 v74, 0, v74, vcc
	v_cndmask_b32_e32 v75, 0, v75, vcc
	v_cndmask_b32_e32 v76, 0, v76, vcc
	v_cndmask_b32_e32 v77, 0, v77, vcc
	v_cndmask_b32_e32 v78, 0, v78, vcc
	v_cndmask_b32_e32 v79, 0, v79, vcc
.Ltp_nz_7:
	ds_write_b32 v22, v64
	ds_write_b32 v22, v65 offset:1040
	ds_write_b32 v22, v66 offset:2080
	ds_write_b32 v22, v67 offset:3120
	ds_write_b32 v22, v68 offset:4160
	ds_write_b32 v22, v69 offset:5200
	ds_write_b32 v22, v70 offset:6240
	ds_write_b32 v22, v71 offset:7280
	ds_write_b32 v22, v72 offset:8320
	ds_write_b32 v22, v73 offset:9360
	ds_write_b32 v22, v74 offset:10400
	ds_write_b32 v22, v75 offset:11440
	ds_write_b32 v22, v76 offset:12480
	ds_write_b32 v22, v77 offset:13520
	ds_write_b32 v22, v78 offset:14560
	ds_write_b32 v22, v79 offset:15600
	v_mov_b32_e32 v3, s85
	v_mad_u32_u24 v2, v112, v3, v113
	s_mov_b64 s[94:95], s[86:87]
	s_waitcnt lgkmcnt(0)
	s_barrier
	ds_read2_b32 v[4:5], v24 offset1:65
	ds_read2_b32 v[6:7], v24 offset0:130 offset1:195
	ds_read2_b32 v[8:9], v25 offset0:4 offset1:69
	ds_read2_b32 v[10:11], v25 offset0:134 offset1:199
	ds_read2_b32 v[12:13], v26 offset0:8 offset1:73
	ds_read2_b32 v[14:15], v26 offset0:138 offset1:203
	ds_read2_b32 v[16:17], v27 offset0:12 offset1:77
	ds_read2_b32 v[18:19], v27 offset0:142 offset1:207
	s_waitcnt lgkmcnt(4)
	v_cvt_pk_bf16_f32 v4, v4, v5
	v_cvt_pk_bf16_f32 v5, v6, v7
	v_cvt_pk_bf16_f32 v6, v8, v9
	v_cvt_pk_bf16_f32 v7, v10, v11
	global_store_dwordx4 v2, v[4:7], s[94:95]
	s_waitcnt lgkmcnt(0)
	v_cvt_pk_bf16_f32 v8, v12, v13
	v_cvt_pk_bf16_f32 v9, v14, v15
	v_cvt_pk_bf16_f32 v10, v16, v17
	v_cvt_pk_bf16_f32 v11, v18, v19
	global_store_dwordx4 v2, v[8:11], s[94:95] offset:16
	s_waitcnt vmcnt(6)
	s_cmpk_ge_i32 s88, 0x40
	s_cbranch_scc1 .Ltp_nz_8
	v_cmp_gt_i32_e32 vcc, s88, v20
	v_cndmask_b32_e32 v96, 0, v96, vcc
	v_cndmask_b32_e32 v97, 0, v97, vcc
	v_cndmask_b32_e32 v98, 0, v98, vcc
	v_cndmask_b32_e32 v99, 0, v99, vcc
	v_cndmask_b32_e32 v100, 0, v100, vcc
	v_cndmask_b32_e32 v101, 0, v101, vcc
	v_cndmask_b32_e32 v102, 0, v102, vcc
	v_cndmask_b32_e32 v103, 0, v103, vcc
	v_cndmask_b32_e32 v104, 0, v104, vcc
	v_cndmask_b32_e32 v105, 0, v105, vcc
	v_cndmask_b32_e32 v106, 0, v106, vcc
	v_cndmask_b32_e32 v107, 0, v107, vcc
	v_cndmask_b32_e32 v108, 0, v108, vcc
	v_cndmask_b32_e32 v109, 0, v109, vcc
	v_cndmask_b32_e32 v110, 0, v110, vcc
	v_cndmask_b32_e32 v111, 0, v111, vcc
.Ltp_nz_8:
	ds_write_b32 v23, v96
	ds_write_b32 v23, v97 offset:1040
	ds_write_b32 v23, v98 offset:2080
	ds_write_b32 v23, v99 offset:3120
	ds_write_b32 v23, v100 offset:4160
	ds_write_b32 v23, v101 offset:5200
	ds_write_b32 v23, v102 offset:6240
	ds_write_b32 v23, v103 offset:7280
	ds_write_b32 v23, v104 offset:8320
	ds_write_b32 v23, v105 offset:9360
	ds_write_b32 v23, v106 offset:10400
	ds_write_b32 v23, v107 offset:11440
	ds_write_b32 v23, v108 offset:12480
	ds_write_b32 v23, v109 offset:13520
	ds_write_b32 v23, v110 offset:14560
	ds_write_b32 v23, v111 offset:15600
	v_mov_b32_e32 v3, s89
	v_mad_u32_u24 v2, v112, v3, v113
	s_mov_b64 s[94:95], s[90:91]
	s_waitcnt lgkmcnt(0)
	s_barrier
	ds_read2_b32 v[4:5], v28 offset1:65
	ds_read2_b32 v[6:7], v28 offset0:130 offset1:195
	ds_read2_b32 v[8:9], v29 offset0:4 offset1:69
	ds_read2_b32 v[10:11], v29 offset0:134 offset1:199
	ds_read2_b32 v[12:13], v30 offset0:8 offset1:73
	ds_read2_b32 v[14:15], v30 offset0:138 offset1:203
	ds_read2_b32 v[16:17], v31 offset0:12 offset1:77
	ds_read2_b32 v[18:19], v31 offset0:142 offset1:207
	s_waitcnt lgkmcnt(4)
	v_cvt_pk_bf16_f32 v4, v4, v5
	v_cvt_pk_bf16_f32 v5, v6, v7
	v_cvt_pk_bf16_f32 v6, v8, v9
	v_cvt_pk_bf16_f32 v7, v10, v11
	global_store_dwordx4 v2, v[4:7], s[94:95]
	s_waitcnt lgkmcnt(0)
	v_cvt_pk_bf16_f32 v8, v12, v13
	v_cvt_pk_bf16_f32 v9, v14, v15
	v_cvt_pk_bf16_f32 v10, v16, v17
	v_cvt_pk_bf16_f32 v11, v18, v19
	global_store_dwordx4 v2, v[8:11], s[94:95] offset:16
	s_branch .Ltp_done

.Ltp_nz_48:
	ds_write_b32 v23, v96
	ds_write_b32 v23, v97 offset:1040
	ds_write_b32 v23, v98 offset:2080
	ds_write_b32 v23, v99 offset:3120
	ds_write_b32 v23, v100 offset:4160
	ds_write_b32 v23, v101 offset:5200
	ds_write_b32 v23, v102 offset:6240
	ds_write_b32 v23, v103 offset:7280
	ds_write_b32 v23, v104 offset:8320
	ds_write_b32 v23, v105 offset:9360
	ds_write_b32 v23, v106 offset:10400
	ds_write_b32 v23, v107 offset:11440
	ds_write_b32 v23, v108 offset:12480
	ds_write_b32 v23, v109 offset:13520
	ds_write_b32 v23, v110 offset:14560
	ds_write_b32 v23, v111 offset:15600
	v_mov_b32_e32 v3, s89
	v_mad_u32_u24 v2, v112, v3, v113
	s_mov_b64 s[94:95], s[90:91]
	s_waitcnt lgkmcnt(0)
	s_barrier
	ds_read2_b32 v[4:5], v28 offset1:65
	ds_read2_b32 v[6:7], v28 offset0:130 offset1:195
	ds_read2_b32 v[8:9], v29 offset0:4 offset1:69
	ds_read2_b32 v[10:11], v29 offset0:134 offset1:199
	ds_read2_b32 v[12:13], v30 offset0:8 offset1:73
	ds_read2_b32 v[14:15], v30 offset0:138 offset1:203
	ds_read2_b32 v[16:17], v31 offset0:12 offset1:77
	ds_read2_b32 v[18:19], v31 offset0:142 offset1:207
	s_waitcnt lgkmcnt(4)
	v_cvt_pk_bf16_f32 v4, v4, v5
	v_cvt_pk_bf16_f32 v5, v6, v7
	v_cvt_pk_bf16_f32 v6, v8, v9
	v_cvt_pk_bf16_f32 v7, v10, v11
	global_store_dwordx4 v2, v[4:7], s[94:95]
	s_waitcnt lgkmcnt(0)
	v_cvt_pk_bf16_f32 v8, v12, v13
	v_cvt_pk_bf16_f32 v9, v14, v15
	v_cvt_pk_bf16_f32 v10, v16, v17
	v_cvt_pk_bf16_f32 v11, v18, v19
	global_store_dwordx4 v2, v[8:11], s[94:95] offset:16
.Ltp_done:
	s_waitcnt lgkmcnt(0)
	s_barrier

.LBB0_195:
	v_add_u32_e32 v7, s0, v18
	v_ashrrev_i32_e32 v8, 9, v7
	v_bfe_u32 v7, v7, 5, 4
	v_add_u32_e32 v9, v8, v4
	v_lshl_add_u32 v10, v7, 8, v5
	v_lshl_add_u32 v9, v9, 9, v6
	ds_read_b128 v[20:23], v10 offset:16384
	ds_read_b128 v[24:27], v10 offset:16400
	ds_read_b128 v[28:31], v10 offset:20480
	ds_read_b128 v[32:35], v10 offset:20496
	ds_read_b128 v[36:39], v9 offset:32768
	ds_read_b128 v[40:43], v9 offset:32784
	ds_read_b128 v[44:47], v9 offset:32800
	ds_read_b128 v[48:51], v9 offset:32816
	v_lshl_add_u32 v8, v8, 4, s6
	s_waitcnt lgkmcnt(3)
	v_mov_b32_e32 v52, v37
	v_mov_b32_e32 v53, v39
	v_mov_b32_e32 v37, v38
	s_waitcnt lgkmcnt(2)
	v_mov_b32_e32 v38, v41
	v_mov_b32_e32 v39, v43
	v_mov_b32_e32 v41, v42
	s_waitcnt lgkmcnt(1)
	v_mov_b32_e32 v42, v45
	v_mov_b32_e32 v43, v47
	v_mov_b32_e32 v45, v46
	s_waitcnt lgkmcnt(0)
	v_mov_b32_e32 v46, v49
	v_mov_b32_e32 v47, v51
	v_mov_b32_e32 v49, v50
	v_pk_mul_f32 v[50:51], v[36:37], v[28:29]
	v_pk_mul_f32 v[28:29], v[52:53], v[28:29]
	v_pk_mul_f32 v[54:55], v[40:41], v[30:31]
	v_pk_mul_f32 v[30:31], v[38:39], v[30:31]
	v_pk_mul_f32 v[56:57], v[44:45], v[32:33]
	v_pk_mul_f32 v[32:33], v[42:43], v[32:33]
	v_pk_mul_f32 v[58:59], v[48:49], v[34:35]
	v_pk_mul_f32 v[34:35], v[46:47], v[34:35]
	v_or_b32_e32 v7, v8, v7
	s_movk_i32 s1, 0x600
	v_pk_fma_f32 v[50:51], v[52:53], v[20:21], v[50:51]
	v_pk_fma_f32 v[20:21], v[36:37], v[20:21], v[28:29] neg_lo:[0,0,1] neg_hi:[0,0,1]
	v_pk_fma_f32 v[28:29], v[38:39], v[22:23], v[54:55]
	v_pk_fma_f32 v[22:23], v[40:41], v[22:23], v[30:31] neg_lo:[0,0,1] neg_hi:[0,0,1]
	v_pk_fma_f32 v[30:31], v[42:43], v[24:25], v[56:57]
	v_pk_fma_f32 v[24:25], v[44:45], v[24:25], v[32:33] neg_lo:[0,0,1] neg_hi:[0,0,1]
	v_pk_fma_f32 v[32:33], v[46:47], v[26:27], v[58:59]
	v_pk_fma_f32 v[26:27], v[48:49], v[26:27], v[34:35] neg_lo:[0,0,1] neg_hi:[0,0,1]
	s_addk_i32 s0, 0x100
	v_mad_i64_i32 v[8:9], s[10:11], v7, s1, v[2:3]
	v_cndmask_b32_e64 v7, -v51, v21, vcc
	v_cndmask_b32_e64 v10, -v50, v20, vcc
	v_cndmask_b32_e64 v19, -v29, v23, vcc
	v_cndmask_b32_e64 v21, -v28, v22, vcc
	v_cndmask_b32_e64 v22, -v31, v25, vcc
	v_cndmask_b32_e64 v23, -v30, v24, vcc
	v_cndmask_b32_e64 v24, -v33, v27, vcc
	v_cndmask_b32_e64 v25, -v32, v26, vcc
	s_cmpk_eq_i32 s0, 0x800
	v_cvt_pk_bf16_f32 v20, v10, v7
	v_cvt_pk_bf16_f32 v21, v21, v19
	v_cvt_pk_bf16_f32 v22, v23, v22
	v_cvt_pk_bf16_f32 v23, v25, v24
	global_store_dwordx4 v[8:9], v[20:23], off offset:1024
	s_cbranch_scc0 .LBB0_195
	v_readlane_b32 s76, v253, 42
	v_readlane_b32 s78, v253, 44
	v_readlane_b32 s79, v253, 45
	v_readlane_b32 s77, v253, 43
	v_readlane_b32 s80, v253, 46
	v_readlane_b32 s81, v253, 47
	v_readlane_b32 s82, v253, 48
	v_readlane_b32 s83, v253, 49
	v_readlane_b32 s84, v253, 50
	v_readlane_b32 s85, v253, 51
	v_readlane_b32 s86, v253, 52
	v_readlane_b32 s87, v253, 53
	v_readlane_b32 s88, v253, 54
	v_readlane_b32 s89, v253, 55
	v_readlane_b32 s90, v253, 56
	v_readlane_b32 s91, v253, 57
	v_and_b32_e32 v2, 15, v18
	v_bfe_u32 v3, v18, 4, 1
	v_bfe_u32 v4, v18, 5, 1
	v_lshrrev_b32_e32 v5, 6, v18
	v_lshlrev_b32_e32 v6, 9, v5
	v_lshl_add_u32 v6, v4, 8, v6
	v_add_u32_e32 v20, s44, v6
	v_mul_u32_u24_e32 v6, 0x110, v2
	v_lshl_add_u32 v6, v4, 7, v6
	v_add_u32_e32 v21, s41, v6
	v_lshlrev_b32_e32 v6, 13, v3
	v_lshl_add_u32 v6, v4, 11, v6
	v_lshl_add_u32 v6, v2, 2, v6
	v_add_u32_e32 v22, s41, v6
	v_cmp_ne_u32_e64 s[0:1], 0, v3
	v_mov_b32_e32 v7, 1.0
	v_cndmask_b32_e64 v7, v7, -1.0, s[0:1]
	v_bfe_u32 v6, v18, 4, 2
	v_lshlrev_b32_e32 v6, 8, v6
	v_lshl_add_u32 v6, v5, 10, v6
	v_lshl_add_u32 v6, v2, 2, v6
	v_add_u32_e32 v23, s41, v6
	v_and_b32_e32 v8, 0x7f, v18
	v_lshrrev_b32_e32 v9, 7, v18
	v_lshlrev_b32_e32 v10, 5, v8
	v_lshl_add_u32 v10, v9, 12, v10
	v_add_u32_e32 v10, s43, v10
	ds_read_b128 v[32:35], v10
	ds_read_b128 v[36:39], v10 offset:16
	v_lshrrev_b32_e32 v10, 3, v8
	v_and_b32_e32 v8, 7, v8
	v_mul_u32_u24_e32 v10, 0x110, v10
	v_lshl_add_u32 v10, v8, 5, v10
	v_mul_u32_u24_e32 v9, 0x1100, v9
	v_add3_u32 v10, s41, v10, v9
	s_waitcnt lgkmcnt(0)
	ds_write_b128 v10, v[32:35] offset:45056
	ds_write_b128 v10, v[36:39] offset:45072
	s_waitcnt lgkmcnt(0)
	s_barrier
	ds_read_b128 v[76:79], v21 offset:45056
	ds_read_b128 v[80:83], v21 offset:45072
	ds_read_b128 v[84:87], v21 offset:45088
	ds_read_b128 v[88:91], v21 offset:45104
	ds_read_b128 v[92:95], v21 offset:45120
	ds_read_b128 v[96:99], v21 offset:45136
	ds_read_b128 v[100:103], v21 offset:45152
	ds_read_b128 v[104:107], v21 offset:45168
	ds_read_b128 v[108:111], v21 offset:49408
	ds_read_b128 v[112:115], v21 offset:49424
	ds_read_b128 v[116:119], v21 offset:49440
	ds_read_b128 v[120:123], v21 offset:49456
	ds_read_b128 v[124:127], v21 offset:49472
	ds_read_b128 v[128:131], v21 offset:49488
	ds_read_b128 v[132:135], v21 offset:49504
	ds_read_b128 v[136:139], v21 offset:49520
	s_waitcnt lgkmcnt(0)
	v_mul_f32_e32 v76, v76, v7
	v_mul_f32_e32 v77, v77, v7
	v_mul_f32_e32 v78, v78, v7
	v_mul_f32_e32 v79, v79, v7
	v_mul_f32_e32 v80, v80, v7
	v_mul_f32_e32 v81, v81, v7
	v_mul_f32_e32 v82, v82, v7
	v_mul_f32_e32 v83, v83, v7
	v_mul_f32_e32 v84, v84, v7
	v_mul_f32_e32 v85, v85, v7
	v_mul_f32_e32 v86, v86, v7
	v_mul_f32_e32 v87, v87, v7
	v_mul_f32_e32 v88, v88, v7
	v_mul_f32_e32 v89, v89, v7
	v_mul_f32_e32 v90, v90, v7
	v_mul_f32_e32 v91, v91, v7
	v_mul_f32_e32 v92, v92, v7
	v_mul_f32_e32 v93, v93, v7
	v_mul_f32_e32 v94, v94, v7
	v_mul_f32_e32 v95, v95, v7
	v_mul_f32_e32 v96, v96, v7
	v_mul_f32_e32 v97, v97, v7
	v_mul_f32_e32 v98, v98, v7
	v_mul_f32_e32 v99, v99, v7
	v_mul_f32_e32 v100, v100, v7
	v_mul_f32_e32 v101, v101, v7
	v_mul_f32_e32 v102, v102, v7
	v_mul_f32_e32 v103, v103, v7
	v_mul_f32_e32 v104, v104, v7
	v_mul_f32_e32 v105, v105, v7
	v_mul_f32_e32 v106, v106, v7
	v_mul_f32_e32 v107, v107, v7
	v_mov_b32_e32 v24, 0
	v_mov_b32_e32 v25, 0
	v_mov_b32_e32 v26, 0
	v_mov_b32_e32 v27, 0
	ds_read_b64 v[32:33], v20 offset:0
	ds_read_b32 v40, v22 offset:0
	ds_read_b64 v[34:35], v20 offset:8
	ds_read_b32 v41, v22 offset:64
	ds_read_b64 v[36:37], v20 offset:16
	ds_read_b32 v42, v22 offset:128
	ds_read_b64 v[38:39], v20 offset:24
	ds_read_b32 v43, v22 offset:192
	ds_read_b64 v[44:45], v20 offset:32
	ds_read_b32 v52, v22 offset:256
	ds_read_b64 v[46:47], v20 offset:40
	ds_read_b32 v53, v22 offset:320
	ds_read_b64 v[48:49], v20 offset:48
	ds_read_b32 v54, v22 offset:384
	ds_read_b64 v[50:51], v20 offset:56
	ds_read_b32 v55, v22 offset:448
	s_waitcnt lgkmcnt(8)
	v_cndmask_b32_e64 v8, v32, v33, s[0:1]
	v_cndmask_b32_e64 v9, v33, v32, s[0:1]
	v_mul_f32_e32 v9, v108, v9
	v_fma_f32 v56, v76, v8, -v9
	v_cndmask_b32_e64 v8, v34, v35, s[0:1]
	v_cndmask_b32_e64 v9, v35, v34, s[0:1]
	v_mul_f32_e32 v9, v109, v9
	v_fma_f32 v57, v77, v8, -v9
	v_cndmask_b32_e64 v8, v36, v37, s[0:1]
	v_cndmask_b32_e64 v9, v37, v36, s[0:1]
	v_mul_f32_e32 v9, v110, v9
	v_fma_f32 v58, v78, v8, -v9
	v_cndmask_b32_e64 v8, v38, v39, s[0:1]
	v_cndmask_b32_e64 v9, v39, v38, s[0:1]
	v_mul_f32_e32 v9, v111, v9
	v_fma_f32 v59, v79, v8, -v9
	s_nop 1
	v_mfma_f32_16x16x4_f32 v[24:27], v56, v40, v[24:27]
	v_mfma_f32_16x16x4_f32 v[24:27], v57, v41, v[24:27]
	v_mfma_f32_16x16x4_f32 v[24:27], v58, v42, v[24:27]
	v_mfma_f32_16x16x4_f32 v[24:27], v59, v43, v[24:27]
	ds_read_b64 v[32:33], v20 offset:64
	ds_read_b32 v40, v22 offset:512
	ds_read_b64 v[34:35], v20 offset:72
	ds_read_b32 v41, v22 offset:576
	ds_read_b64 v[36:37], v20 offset:80
	ds_read_b32 v42, v22 offset:640
	ds_read_b64 v[38:39], v20 offset:88
	ds_read_b32 v43, v22 offset:704
	s_waitcnt lgkmcnt(8)
	v_cndmask_b32_e64 v8, v44, v45, s[0:1]
	v_cndmask_b32_e64 v9, v45, v44, s[0:1]
	v_mul_f32_e32 v9, v112, v9
	v_fma_f32 v56, v80, v8, -v9
	v_cndmask_b32_e64 v8, v46, v47, s[0:1]
	v_cndmask_b32_e64 v9, v47, v46, s[0:1]
	v_mul_f32_e32 v9, v113, v9
	v_fma_f32 v57, v81, v8, -v9
	v_cndmask_b32_e64 v8, v48, v49, s[0:1]
	v_cndmask_b32_e64 v9, v49, v48, s[0:1]
	v_mul_f32_e32 v9, v114, v9
	v_fma_f32 v58, v82, v8, -v9
	v_cndmask_b32_e64 v8, v50, v51, s[0:1]
	v_cndmask_b32_e64 v9, v51, v50, s[0:1]
	v_mul_f32_e32 v9, v115, v9
	v_fma_f32 v59, v83, v8, -v9
	s_nop 1
	v_mfma_f32_16x16x4_f32 v[24:27], v56, v52, v[24:27]
	v_mfma_f32_16x16x4_f32 v[24:27], v57, v53, v[24:27]
	v_mfma_f32_16x16x4_f32 v[24:27], v58, v54, v[24:27]
	v_mfma_f32_16x16x4_f32 v[24:27], v59, v55, v[24:27]
	ds_read_b64 v[44:45], v20 offset:96
	ds_read_b32 v52, v22 offset:768
	ds_read_b64 v[46:47], v20 offset:104
	ds_read_b32 v53, v22 offset:832
	ds_read_b64 v[48:49], v20 offset:112
	ds_read_b32 v54, v22 offset:896
	ds_read_b64 v[50:51], v20 offset:120
	ds_read_b32 v55, v22 offset:960
	s_waitcnt lgkmcnt(8)
	v_cndmask_b32_e64 v8, v32, v33, s[0:1]
	v_cndmask_b32_e64 v9, v33, v32, s[0:1]
	v_mul_f32_e32 v9, v116, v9
	v_fma_f32 v56, v84, v8, -v9
	v_cndmask_b32_e64 v8, v34, v35, s[0:1]
	v_cndmask_b32_e64 v9, v35, v34, s[0:1]
	v_mul_f32_e32 v9, v117, v9
	v_fma_f32 v57, v85, v8, -v9
	v_cndmask_b32_e64 v8, v36, v37, s[0:1]
	v_cndmask_b32_e64 v9, v37, v36, s[0:1]
	v_mul_f32_e32 v9, v118, v9
	v_fma_f32 v58, v86, v8, -v9
	v_cndmask_b32_e64 v8, v38, v39, s[0:1]
	v_cndmask_b32_e64 v9, v39, v38, s[0:1]
	v_mul_f32_e32 v9, v119, v9
	v_fma_f32 v59, v87, v8, -v9
	s_nop 1
	v_mfma_f32_16x16x4_f32 v[24:27], v56, v40, v[24:27]
	v_mfma_f32_16x16x4_f32 v[24:27], v57, v41, v[24:27]
	v_mfma_f32_16x16x4_f32 v[24:27], v58, v42, v[24:27]
	v_mfma_f32_16x16x4_f32 v[24:27], v59, v43, v[24:27]
	ds_read_b64 v[32:33], v20 offset:128
	ds_read_b32 v40, v22 offset:1024
	ds_read_b64 v[34:35], v20 offset:136
	ds_read_b32 v41, v22 offset:1088
	ds_read_b64 v[36:37], v20 offset:144
	ds_read_b32 v42, v22 offset:1152
	ds_read_b64 v[38:39], v20 offset:152
	ds_read_b32 v43, v22 offset:1216
	s_waitcnt lgkmcnt(8)
	v_cndmask_b32_e64 v8, v44, v45, s[0:1]
	v_cndmask_b32_e64 v9, v45, v44, s[0:1]
	v_mul_f32_e32 v9, v120, v9
	v_fma_f32 v56, v88, v8, -v9
	v_cndmask_b32_e64 v8, v46, v47, s[0:1]
	v_cndmask_b32_e64 v9, v47, v46, s[0:1]
	v_mul_f32_e32 v9, v121, v9
	v_fma_f32 v57, v89, v8, -v9
	v_cndmask_b32_e64 v8, v48, v49, s[0:1]
	v_cndmask_b32_e64 v9, v49, v48, s[0:1]
	v_mul_f32_e32 v9, v122, v9
	v_fma_f32 v58, v90, v8, -v9
	v_cndmask_b32_e64 v8, v50, v51, s[0:1]
	v_cndmask_b32_e64 v9, v51, v50, s[0:1]
	v_mul_f32_e32 v9, v123, v9
	v_fma_f32 v59, v91, v8, -v9
	s_nop 1
	v_mfma_f32_16x16x4_f32 v[24:27], v56, v52, v[24:27]
	v_mfma_f32_16x16x4_f32 v[24:27], v57, v53, v[24:27]
	v_mfma_f32_16x16x4_f32 v[24:27], v58, v54, v[24:27]
	v_mfma_f32_16x16x4_f32 v[24:27], v59, v55, v[24:27]
	ds_read_b64 v[44:45], v20 offset:160
	ds_read_b32 v52, v22 offset:1280
	ds_read_b64 v[46:47], v20 offset:168
	ds_read_b32 v53, v22 offset:1344
	ds_read_b64 v[48:49], v20 offset:176
	ds_read_b32 v54, v22 offset:1408
	ds_read_b64 v[50:51], v20 offset:184
	ds_read_b32 v55, v22 offset:1472
	s_waitcnt lgkmcnt(8)
	v_cndmask_b32_e64 v8, v32, v33, s[0:1]
	v_cndmask_b32_e64 v9, v33, v32, s[0:1]
	v_mul_f32_e32 v9, v124, v9
	v_fma_f32 v56, v92, v8, -v9
	v_cndmask_b32_e64 v8, v34, v35, s[0:1]
	v_cndmask_b32_e64 v9, v35, v34, s[0:1]
	v_mul_f32_e32 v9, v125, v9
	v_fma_f32 v57, v93, v8, -v9
	v_cndmask_b32_e64 v8, v36, v37, s[0:1]
	v_cndmask_b32_e64 v9, v37, v36, s[0:1]
	v_mul_f32_e32 v9, v126, v9
	v_fma_f32 v58, v94, v8, -v9
	v_cndmask_b32_e64 v8, v38, v39, s[0:1]
	v_cndmask_b32_e64 v9, v39, v38, s[0:1]
	v_mul_f32_e32 v9, v127, v9
	v_fma_f32 v59, v95, v8, -v9
	s_nop 1
	v_mfma_f32_16x16x4_f32 v[24:27], v56, v40, v[24:27]
	v_mfma_f32_16x16x4_f32 v[24:27], v57, v41, v[24:27]
	v_mfma_f32_16x16x4_f32 v[24:27], v58, v42, v[24:27]
	v_mfma_f32_16x16x4_f32 v[24:27], v59, v43, v[24:27]
	ds_read_b64 v[32:33], v20 offset:192
	ds_read_b32 v40, v22 offset:1536
	ds_read_b64 v[34:35], v20 offset:200
	ds_read_b32 v41, v22 offset:1600
	ds_read_b64 v[36:37], v20 offset:208
	ds_read_b32 v42, v22 offset:1664
	ds_read_b64 v[38:39], v20 offset:216
	ds_read_b32 v43, v22 offset:1728
	s_waitcnt lgkmcnt(8)
	v_cndmask_b32_e64 v8, v44, v45, s[0:1]
	v_cndmask_b32_e64 v9, v45, v44, s[0:1]
	v_mul_f32_e32 v9, v128, v9
	v_fma_f32 v56, v96, v8, -v9
	v_cndmask_b32_e64 v8, v46, v47, s[0:1]
	v_cndmask_b32_e64 v9, v47, v46, s[0:1]
	v_mul_f32_e32 v9, v129, v9
	v_fma_f32 v57, v97, v8, -v9
	v_cndmask_b32_e64 v8, v48, v49, s[0:1]
	v_cndmask_b32_e64 v9, v49, v48, s[0:1]
	v_mul_f32_e32 v9, v130, v9
	v_fma_f32 v58, v98, v8, -v9
	v_cndmask_b32_e64 v8, v50, v51, s[0:1]
	v_cndmask_b32_e64 v9, v51, v50, s[0:1]
	v_mul_f32_e32 v9, v131, v9
	v_fma_f32 v59, v99, v8, -v9
	s_nop 1
	v_mfma_f32_16x16x4_f32 v[24:27], v56, v52, v[24:27]
	v_mfma_f32_16x16x4_f32 v[24:27], v57, v53, v[24:27]
	v_mfma_f32_16x16x4_f32 v[24:27], v58, v54, v[24:27]
	v_mfma_f32_16x16x4_f32 v[24:27], v59, v55, v[24:27]
	ds_read_b64 v[44:45], v20 offset:224
	ds_read_b32 v52, v22 offset:1792
	ds_read_b64 v[46:47], v20 offset:232
	ds_read_b32 v53, v22 offset:1856
	ds_read_b64 v[48:49], v20 offset:240
	ds_read_b32 v54, v22 offset:1920
	ds_read_b64 v[50:51], v20 offset:248
	ds_read_b32 v55, v22 offset:1984
	s_waitcnt lgkmcnt(8)
	v_cndmask_b32_e64 v8, v32, v33, s[0:1]
	v_cndmask_b32_e64 v9, v33, v32, s[0:1]
	v_mul_f32_e32 v9, v132, v9
	v_fma_f32 v56, v100, v8, -v9
	v_cndmask_b32_e64 v8, v34, v35, s[0:1]
	v_cndmask_b32_e64 v9, v35, v34, s[0:1]
	v_mul_f32_e32 v9, v133, v9
	v_fma_f32 v57, v101, v8, -v9
	v_cndmask_b32_e64 v8, v36, v37, s[0:1]
	v_cndmask_b32_e64 v9, v37, v36, s[0:1]
	v_mul_f32_e32 v9, v134, v9
	v_fma_f32 v58, v102, v8, -v9
	v_cndmask_b32_e64 v8, v38, v39, s[0:1]
	v_cndmask_b32_e64 v9, v39, v38, s[0:1]
	v_mul_f32_e32 v9, v135, v9
	v_fma_f32 v59, v103, v8, -v9
	s_nop 1
	v_mfma_f32_16x16x4_f32 v[24:27], v56, v40, v[24:27]
	v_mfma_f32_16x16x4_f32 v[24:27], v57, v41, v[24:27]
	v_mfma_f32_16x16x4_f32 v[24:27], v58, v42, v[24:27]
	v_mfma_f32_16x16x4_f32 v[24:27], v59, v43, v[24:27]
	s_waitcnt lgkmcnt(0)
	v_cndmask_b32_e64 v8, v44, v45, s[0:1]
	v_cndmask_b32_e64 v9, v45, v44, s[0:1]
	v_mul_f32_e32 v9, v136, v9
	v_fma_f32 v56, v104, v8, -v9
	v_cndmask_b32_e64 v8, v46, v47, s[0:1]
	v_cndmask_b32_e64 v9, v47, v46, s[0:1]
	v_mul_f32_e32 v9, v137, v9
	v_fma_f32 v57, v105, v8, -v9
	v_cndmask_b32_e64 v8, v48, v49, s[0:1]
	v_cndmask_b32_e64 v9, v49, v48, s[0:1]
	v_mul_f32_e32 v9, v138, v9
	v_fma_f32 v58, v106, v8, -v9
	v_cndmask_b32_e64 v8, v50, v51, s[0:1]
	v_cndmask_b32_e64 v9, v51, v50, s[0:1]
	v_mul_f32_e32 v9, v139, v9
	v_fma_f32 v59, v107, v8, -v9
	s_nop 1
	v_mfma_f32_16x16x4_f32 v[24:27], v56, v52, v[24:27]
	v_mfma_f32_16x16x4_f32 v[24:27], v57, v53, v[24:27]
	v_mfma_f32_16x16x4_f32 v[24:27], v58, v54, v[24:27]
	v_mfma_f32_16x16x4_f32 v[24:27], v59, v55, v[24:27]
	s_nop 15
	ds_write_b32 v23, v24 offset:36864
	ds_write_b32 v23, v25 offset:36928
	ds_write_b32 v23, v26 offset:36992
	ds_write_b32 v23, v27 offset:37056
	v_mov_b32_e32 v24, 0
	v_mov_b32_e32 v25, 0
	v_mov_b32_e32 v26, 0
	v_mov_b32_e32 v27, 0
	ds_read_b64 v[32:33], v20 offset:2048
	ds_read_b32 v40, v22 offset:4096
	ds_read_b64 v[34:35], v20 offset:2056
	ds_read_b32 v41, v22 offset:4160
	ds_read_b64 v[36:37], v20 offset:2064
	ds_read_b32 v42, v22 offset:4224
	ds_read_b64 v[38:39], v20 offset:2072
	ds_read_b32 v43, v22 offset:4288
	ds_read_b64 v[44:45], v20 offset:2080
	ds_read_b32 v52, v22 offset:4352
	ds_read_b64 v[46:47], v20 offset:2088
	ds_read_b32 v53, v22 offset:4416
	ds_read_b64 v[48:49], v20 offset:2096
	ds_read_b32 v54, v22 offset:4480
	ds_read_b64 v[50:51], v20 offset:2104
	ds_read_b32 v55, v22 offset:4544
	s_waitcnt lgkmcnt(8)
	v_cndmask_b32_e64 v8, v32, v33, s[0:1]
	v_cndmask_b32_e64 v9, v33, v32, s[0:1]
	v_mul_f32_e32 v9, v108, v9
	v_fma_f32 v56, v76, v8, -v9
	v_cndmask_b32_e64 v8, v34, v35, s[0:1]
	v_cndmask_b32_e64 v9, v35, v34, s[0:1]
	v_mul_f32_e32 v9, v109, v9
	v_fma_f32 v57, v77, v8, -v9
	v_cndmask_b32_e64 v8, v36, v37, s[0:1]
	v_cndmask_b32_e64 v9, v37, v36, s[0:1]
	v_mul_f32_e32 v9, v110, v9
	v_fma_f32 v58, v78, v8, -v9
	v_cndmask_b32_e64 v8, v38, v39, s[0:1]
	v_cndmask_b32_e64 v9, v39, v38, s[0:1]
	v_mul_f32_e32 v9, v111, v9
	v_fma_f32 v59, v79, v8, -v9
	s_nop 1
	v_mfma_f32_16x16x4_f32 v[24:27], v56, v40, v[24:27]
	v_mfma_f32_16x16x4_f32 v[24:27], v57, v41, v[24:27]
	v_mfma_f32_16x16x4_f32 v[24:27], v58, v42, v[24:27]
	v_mfma_f32_16x16x4_f32 v[24:27], v59, v43, v[24:27]
	ds_read_b64 v[32:33], v20 offset:2112
	ds_read_b32 v40, v22 offset:4608
	ds_read_b64 v[34:35], v20 offset:2120
	ds_read_b32 v41, v22 offset:4672
	ds_read_b64 v[36:37], v20 offset:2128
	ds_read_b32 v42, v22 offset:4736
	ds_read_b64 v[38:39], v20 offset:2136
	ds_read_b32 v43, v22 offset:4800
	s_waitcnt lgkmcnt(8)
	v_cndmask_b32_e64 v8, v44, v45, s[0:1]
	v_cndmask_b32_e64 v9, v45, v44, s[0:1]
	v_mul_f32_e32 v9, v112, v9
	v_fma_f32 v56, v80, v8, -v9
	v_cndmask_b32_e64 v8, v46, v47, s[0:1]
	v_cndmask_b32_e64 v9, v47, v46, s[0:1]
	v_mul_f32_e32 v9, v113, v9
	v_fma_f32 v57, v81, v8, -v9
	v_cndmask_b32_e64 v8, v48, v49, s[0:1]
	v_cndmask_b32_e64 v9, v49, v48, s[0:1]
	v_mul_f32_e32 v9, v114, v9
	v_fma_f32 v58, v82, v8, -v9
	v_cndmask_b32_e64 v8, v50, v51, s[0:1]
	v_cndmask_b32_e64 v9, v51, v50, s[0:1]
	v_mul_f32_e32 v9, v115, v9
	v_fma_f32 v59, v83, v8, -v9
	s_nop 1
	v_mfma_f32_16x16x4_f32 v[24:27], v56, v52, v[24:27]
	v_mfma_f32_16x16x4_f32 v[24:27], v57, v53, v[24:27]
	v_mfma_f32_16x16x4_f32 v[24:27], v58, v54, v[24:27]
	v_mfma_f32_16x16x4_f32 v[24:27], v59, v55, v[24:27]
	ds_read_b64 v[44:45], v20 offset:2144
	ds_read_b32 v52, v22 offset:4864
	ds_read_b64 v[46:47], v20 offset:2152
	ds_read_b32 v53, v22 offset:4928
	ds_read_b64 v[48:49], v20 offset:2160
	ds_read_b32 v54, v22 offset:4992
	ds_read_b64 v[50:51], v20 offset:2168
	ds_read_b32 v55, v22 offset:5056
	s_waitcnt lgkmcnt(8)
	v_cndmask_b32_e64 v8, v32, v33, s[0:1]
	v_cndmask_b32_e64 v9, v33, v32, s[0:1]
	v_mul_f32_e32 v9, v116, v9
	v_fma_f32 v56, v84, v8, -v9
	v_cndmask_b32_e64 v8, v34, v35, s[0:1]
	v_cndmask_b32_e64 v9, v35, v34, s[0:1]
	v_mul_f32_e32 v9, v117, v9
	v_fma_f32 v57, v85, v8, -v9
	v_cndmask_b32_e64 v8, v36, v37, s[0:1]
	v_cndmask_b32_e64 v9, v37, v36, s[0:1]
	v_mul_f32_e32 v9, v118, v9
	v_fma_f32 v58, v86, v8, -v9
	v_cndmask_b32_e64 v8, v38, v39, s[0:1]
	v_cndmask_b32_e64 v9, v39, v38, s[0:1]
	v_mul_f32_e32 v9, v119, v9
	v_fma_f32 v59, v87, v8, -v9
	s_nop 1
	v_mfma_f32_16x16x4_f32 v[24:27], v56, v40, v[24:27]
	v_mfma_f32_16x16x4_f32 v[24:27], v57, v41, v[24:27]
	v_mfma_f32_16x16x4_f32 v[24:27], v58, v42, v[24:27]
	v_mfma_f32_16x16x4_f32 v[24:27], v59, v43, v[24:27]
	ds_read_b64 v[32:33], v20 offset:2176
	ds_read_b32 v40, v22 offset:5120
	ds_read_b64 v[34:35], v20 offset:2184
	ds_read_b32 v41, v22 offset:5184
	ds_read_b64 v[36:37], v20 offset:2192
	ds_read_b32 v42, v22 offset:5248
	ds_read_b64 v[38:39], v20 offset:2200
	ds_read_b32 v43, v22 offset:5312
	s_waitcnt lgkmcnt(8)
	v_cndmask_b32_e64 v8, v44, v45, s[0:1]
	v_cndmask_b32_e64 v9, v45, v44, s[0:1]
	v_mul_f32_e32 v9, v120, v9
	v_fma_f32 v56, v88, v8, -v9
	v_cndmask_b32_e64 v8, v46, v47, s[0:1]
	v_cndmask_b32_e64 v9, v47, v46, s[0:1]
	v_mul_f32_e32 v9, v121, v9
	v_fma_f32 v57, v89, v8, -v9
	v_cndmask_b32_e64 v8, v48, v49, s[0:1]
	v_cndmask_b32_e64 v9, v49, v48, s[0:1]
	v_mul_f32_e32 v9, v122, v9
	v_fma_f32 v58, v90, v8, -v9
	v_cndmask_b32_e64 v8, v50, v51, s[0:1]
	v_cndmask_b32_e64 v9, v51, v50, s[0:1]
	v_mul_f32_e32 v9, v123, v9
	v_fma_f32 v59, v91, v8, -v9
	s_nop 1
	v_mfma_f32_16x16x4_f32 v[24:27], v56, v52, v[24:27]
	v_mfma_f32_16x16x4_f32 v[24:27], v57, v53, v[24:27]
	v_mfma_f32_16x16x4_f32 v[24:27], v58, v54, v[24:27]
	v_mfma_f32_16x16x4_f32 v[24:27], v59, v55, v[24:27]
	ds_read_b64 v[44:45], v20 offset:2208
	ds_read_b32 v52, v22 offset:5376
	ds_read_b64 v[46:47], v20 offset:2216
	ds_read_b32 v53, v22 offset:5440
	ds_read_b64 v[48:49], v20 offset:2224
	ds_read_b32 v54, v22 offset:5504
	ds_read_b64 v[50:51], v20 offset:2232
	ds_read_b32 v55, v22 offset:5568
	s_waitcnt lgkmcnt(8)
	v_cndmask_b32_e64 v8, v32, v33, s[0:1]
	v_cndmask_b32_e64 v9, v33, v32, s[0:1]
	v_mul_f32_e32 v9, v124, v9
	v_fma_f32 v56, v92, v8, -v9
	v_cndmask_b32_e64 v8, v34, v35, s[0:1]
	v_cndmask_b32_e64 v9, v35, v34, s[0:1]
	v_mul_f32_e32 v9, v125, v9
	v_fma_f32 v57, v93, v8, -v9
	v_cndmask_b32_e64 v8, v36, v37, s[0:1]
	v_cndmask_b32_e64 v9, v37, v36, s[0:1]
	v_mul_f32_e32 v9, v126, v9
	v_fma_f32 v58, v94, v8, -v9
	v_cndmask_b32_e64 v8, v38, v39, s[0:1]
	v_cndmask_b32_e64 v9, v39, v38, s[0:1]
	v_mul_f32_e32 v9, v127, v9
	v_fma_f32 v59, v95, v8, -v9
	s_nop 1
	v_mfma_f32_16x16x4_f32 v[24:27], v56, v40, v[24:27]
	v_mfma_f32_16x16x4_f32 v[24:27], v57, v41, v[24:27]
	v_mfma_f32_16x16x4_f32 v[24:27], v58, v42, v[24:27]
	v_mfma_f32_16x16x4_f32 v[24:27], v59, v43, v[24:27]
	ds_read_b64 v[32:33], v20 offset:2240
	ds_read_b32 v40, v22 offset:5632
	ds_read_b64 v[34:35], v20 offset:2248
	ds_read_b32 v41, v22 offset:5696
	ds_read_b64 v[36:37], v20 offset:2256
	ds_read_b32 v42, v22 offset:5760
	ds_read_b64 v[38:39], v20 offset:2264
	ds_read_b32 v43, v22 offset:5824
	s_waitcnt lgkmcnt(8)
	v_cndmask_b32_e64 v8, v44, v45, s[0:1]
	v_cndmask_b32_e64 v9, v45, v44, s[0:1]
	v_mul_f32_e32 v9, v128, v9
	v_fma_f32 v56, v96, v8, -v9
	v_cndmask_b32_e64 v8, v46, v47, s[0:1]
	v_cndmask_b32_e64 v9, v47, v46, s[0:1]
	v_mul_f32_e32 v9, v129, v9
	v_fma_f32 v57, v97, v8, -v9
	v_cndmask_b32_e64 v8, v48, v49, s[0:1]
	v_cndmask_b32_e64 v9, v49, v48, s[0:1]
	v_mul_f32_e32 v9, v130, v9
	v_fma_f32 v58, v98, v8, -v9
	v_cndmask_b32_e64 v8, v50, v51, s[0:1]
	v_cndmask_b32_e64 v9, v51, v50, s[0:1]
	v_mul_f32_e32 v9, v131, v9
	v_fma_f32 v59, v99, v8, -v9
	s_nop 1
	v_mfma_f32_16x16x4_f32 v[24:27], v56, v52, v[24:27]
	v_mfma_f32_16x16x4_f32 v[24:27], v57, v53, v[24:27]
	v_mfma_f32_16x16x4_f32 v[24:27], v58, v54, v[24:27]
	v_mfma_f32_16x16x4_f32 v[24:27], v59, v55, v[24:27]
	ds_read_b64 v[44:45], v20 offset:2272
	ds_read_b32 v52, v22 offset:5888
	ds_read_b64 v[46:47], v20 offset:2280
	ds_read_b32 v53, v22 offset:5952
	ds_read_b64 v[48:49], v20 offset:2288
	ds_read_b32 v54, v22 offset:6016
	ds_read_b64 v[50:51], v20 offset:2296
	ds_read_b32 v55, v22 offset:6080
	s_waitcnt lgkmcnt(8)
	v_cndmask_b32_e64 v8, v32, v33, s[0:1]
	v_cndmask_b32_e64 v9, v33, v32, s[0:1]
	v_mul_f32_e32 v9, v132, v9
	v_fma_f32 v56, v100, v8, -v9
	v_cndmask_b32_e64 v8, v34, v35, s[0:1]
	v_cndmask_b32_e64 v9, v35, v34, s[0:1]
	v_mul_f32_e32 v9, v133, v9
	v_fma_f32 v57, v101, v8, -v9
	v_cndmask_b32_e64 v8, v36, v37, s[0:1]
	v_cndmask_b32_e64 v9, v37, v36, s[0:1]
	v_mul_f32_e32 v9, v134, v9
	v_fma_f32 v58, v102, v8, -v9
	v_cndmask_b32_e64 v8, v38, v39, s[0:1]
	v_cndmask_b32_e64 v9, v39, v38, s[0:1]
	v_mul_f32_e32 v9, v135, v9
	v_fma_f32 v59, v103, v8, -v9
	s_nop 1
	v_mfma_f32_16x16x4_f32 v[24:27], v56, v40, v[24:27]
	v_mfma_f32_16x16x4_f32 v[24:27], v57, v41, v[24:27]
	v_mfma_f32_16x16x4_f32 v[24:27], v58, v42, v[24:27]
	v_mfma_f32_16x16x4_f32 v[24:27], v59, v43, v[24:27]
	s_waitcnt lgkmcnt(0)
	v_cndmask_b32_e64 v8, v44, v45, s[0:1]
	v_cndmask_b32_e64 v9, v45, v44, s[0:1]
	v_mul_f32_e32 v9, v136, v9
	v_fma_f32 v56, v104, v8, -v9
	v_cndmask_b32_e64 v8, v46, v47, s[0:1]
	v_cndmask_b32_e64 v9, v47, v46, s[0:1]
	v_mul_f32_e32 v9, v137, v9
	v_fma_f32 v57, v105, v8, -v9
	v_cndmask_b32_e64 v8, v48, v49, s[0:1]
	v_cndmask_b32_e64 v9, v49, v48, s[0:1]
	v_mul_f32_e32 v9, v138, v9
	v_fma_f32 v58, v106, v8, -v9
	v_cndmask_b32_e64 v8, v50, v51, s[0:1]
	v_cndmask_b32_e64 v9, v51, v50, s[0:1]
	v_mul_f32_e32 v9, v139, v9
	v_fma_f32 v59, v107, v8, -v9
	s_nop 1
	v_mfma_f32_16x16x4_f32 v[24:27], v56, v52, v[24:27]
	v_mfma_f32_16x16x4_f32 v[24:27], v57, v53, v[24:27]
	v_mfma_f32_16x16x4_f32 v[24:27], v58, v54, v[24:27]
	v_mfma_f32_16x16x4_f32 v[24:27], v59, v55, v[24:27]
	s_nop 15
	ds_write_b32 v23, v24 offset:40960
	ds_write_b32 v23, v25 offset:41024
	ds_write_b32 v23, v26 offset:41088
	ds_write_b32 v23, v27 offset:41152
	s_movk_i32 s0, 0x2000
	v_cmp_gt_i32_e32 vcc, s0, v18
	s_waitcnt lgkmcnt(0)
	s_barrier
	s_and_saveexec_b64 s[6:7], vcc
	s_cbranch_execz .LBB0_106
	s_lshl_b32 s38, s38, 2
	v_and_b32_e32 v2, 1, v18
	v_bfe_u32 v3, v18, 1, 2
	v_bfe_u32 v6, v18, 3, 4
	v_lshrrev_b32_e32 v7, 7, v18
	v_lshlrev_b32_e32 v8, 5, v2
	v_lshl_add_u32 v8, v6, 6, v8
	v_lshl_add_u32 v8, v3, 10, v8
	v_add_u32_e32 v20, s41, v8
	ds_read_b128 v[24:27], v20 offset:36864
	ds_read_b128 v[28:31], v20 offset:36880
	ds_read_b128 v[32:35], v20 offset:40960
	ds_read_b128 v[36:39], v20 offset:40976
	v_add_u32_e32 v9, s38, v3
	v_mul_u32_u24_e32 v8, 0x600, v6
	v_lshl_add_u32 v8, v2, 4, v8
	v_mul_u32_u24_e32 v10, 0x6020, v7
	v_add_u32_e32 v8, v8, v10
	v_lshlrev_b32_e32 v10, 5, v9
	v_sub_u32_e32 v48, v8, v10
	v_add_u32_e32 v49, v8, v10
	v_sub_u32_e32 v50, v7, v9
	v_add_u32_e32 v51, v7, v9
	v_cmp_eq_u32_e32 vcc, 0, v9
	v_mov_b32_e32 v10, 0x4000
	v_cndmask_b32_e32 v51, v51, v10, vcc
	s_waitcnt lgkmcnt(0)
	v_add_f32_e32 v52, v24, v32
	v_add_f32_e32 v53, v25, v33
	v_add_f32_e32 v54, v26, v34
	v_add_f32_e32 v55, v27, v35
	v_add_f32_e32 v56, v28, v36
	v_add_f32_e32 v57, v29, v37
	v_add_f32_e32 v58, v30, v38
	v_add_f32_e32 v59, v31, v39
	v_cndmask_b32_e32 v24, v24, v52, vcc
	v_cndmask_b32_e32 v25, v25, v53, vcc
	v_cndmask_b32_e32 v26, v26, v54, vcc
	v_cndmask_b32_e32 v27, v27, v55, vcc
	v_cndmask_b32_e32 v28, v28, v56, vcc
	v_cndmask_b32_e32 v29, v29, v57, vcc
	v_cndmask_b32_e32 v30, v30, v58, vcc
	v_cndmask_b32_e32 v31, v31, v59, vcc
	v_cvt_pk_bf16_f32 v40, v24, v25
	v_cvt_pk_bf16_f32 v41, v26, v27
	v_cvt_pk_bf16_f32 v42, v28, v29
	v_cvt_pk_bf16_f32 v43, v30, v31
	v_cvt_pk_bf16_f32 v44, v32, v33
	v_cvt_pk_bf16_f32 v45, v34, v35
	v_cvt_pk_bf16_f32 v46, v36, v37
	v_cvt_pk_bf16_f32 v47, v38, v39
	v_cmp_le_i32_e32 vcc, 0, v50
	v_mov_b32_e32 v22, v48
	s_mov_b64 exec, vcc
	global_store_dwordx4 v22, v[40:43], s[4:5]
	s_mov_b64 exec, -1
	v_cmp_ge_i32_e32 vcc, 31, v51
	v_mov_b32_e32 v23, v49
	s_mov_b64 exec, vcc
	global_store_dwordx4 v23, v[44:47], s[4:5]
	s_mov_b64 exec, -1
	v_cmp_le_i32_e32 vcc, -2, v50
	v_add_u32_e32 v22, 0xc040, v48
	s_mov_b64 exec, vcc
	global_store_dwordx4 v22, v[40:43], s[4:5]
	s_mov_b64 exec, -1
	v_cmp_ge_i32_e32 vcc, 29, v51
	v_add_u32_e32 v23, 0xc040, v49
	s_mov_b64 exec, vcc
	global_store_dwordx4 v23, v[44:47], s[4:5]
	s_mov_b64 exec, -1
	v_cmp_le_i32_e32 vcc, -4, v50
	v_add_u32_e32 v22, 0x18080, v48
	s_mov_b64 exec, vcc
	global_store_dwordx4 v22, v[40:43], s[4:5]
	s_mov_b64 exec, -1
	v_cmp_ge_i32_e32 vcc, 27, v51
	v_add_u32_e32 v23, 0x18080, v49
	s_mov_b64 exec, vcc
	global_store_dwordx4 v23, v[44:47], s[4:5]
	s_mov_b64 exec, -1
	v_cmp_le_i32_e32 vcc, -6, v50
	v_add_u32_e32 v22, 0x240c0, v48
	s_mov_b64 exec, vcc
	global_store_dwordx4 v22, v[40:43], s[4:5]
	s_mov_b64 exec, -1
	v_cmp_ge_i32_e32 vcc, 25, v51
	v_add_u32_e32 v23, 0x240c0, v49
	s_mov_b64 exec, vcc
	global_store_dwordx4 v23, v[44:47], s[4:5]
	s_mov_b64 exec, -1
	v_cmp_le_i32_e32 vcc, -8, v50
	v_add_u32_e32 v22, 0x30100, v48
	s_mov_b64 exec, vcc
	global_store_dwordx4 v22, v[40:43], s[4:5]
	s_mov_b64 exec, -1
	v_cmp_ge_i32_e32 vcc, 23, v51
	v_add_u32_e32 v23, 0x30100, v49
	s_mov_b64 exec, vcc
	global_store_dwordx4 v23, v[44:47], s[4:5]
	s_mov_b64 exec, -1
	v_cmp_le_i32_e32 vcc, -10, v50
	v_add_u32_e32 v22, 0x3c140, v48
	s_mov_b64 exec, vcc
	global_store_dwordx4 v22, v[40:43], s[4:5]
	s_mov_b64 exec, -1
	v_cmp_ge_i32_e32 vcc, 21, v51
	v_add_u32_e32 v23, 0x3c140, v49
	s_mov_b64 exec, vcc
	global_store_dwordx4 v23, v[44:47], s[4:5]
	s_mov_b64 exec, -1
	v_cmp_le_i32_e32 vcc, -12, v50
	v_add_u32_e32 v22, 0x48180, v48
	s_mov_b64 exec, vcc
	global_store_dwordx4 v22, v[40:43], s[4:5]
	s_mov_b64 exec, -1
	v_cmp_ge_i32_e32 vcc, 19, v51
	v_add_u32_e32 v23, 0x48180, v49
	s_mov_b64 exec, vcc
	global_store_dwordx4 v23, v[44:47], s[4:5]
	s_mov_b64 exec, -1
	v_cmp_le_i32_e32 vcc, -14, v50
	v_add_u32_e32 v22, 0x541c0, v48
	s_mov_b64 exec, vcc
	global_store_dwordx4 v22, v[40:43], s[4:5]
	s_mov_b64 exec, -1
	v_cmp_ge_i32_e32 vcc, 17, v51
	v_add_u32_e32 v23, 0x541c0, v49
	s_mov_b64 exec, vcc
	global_store_dwordx4 v23, v[44:47], s[4:5]
	s_mov_b64 exec, -1
	v_cmp_le_i32_e32 vcc, -16, v50
	v_add_u32_e32 v22, 0x60200, v48
	s_mov_b64 exec, vcc
	global_store_dwordx4 v22, v[40:43], s[4:5]
	s_mov_b64 exec, -1
	v_cmp_ge_i32_e32 vcc, 15, v51
	v_add_u32_e32 v23, 0x60200, v49
	s_mov_b64 exec, vcc
	global_store_dwordx4 v23, v[44:47], s[4:5]
	s_mov_b64 exec, -1
	v_cmp_le_i32_e32 vcc, -18, v50
	v_add_u32_e32 v22, 0x6c240, v48
	s_mov_b64 exec, vcc
	global_store_dwordx4 v22, v[40:43], s[4:5]
	s_mov_b64 exec, -1
	v_cmp_ge_i32_e32 vcc, 13, v51
	v_add_u32_e32 v23, 0x6c240, v49
	s_mov_b64 exec, vcc
	global_store_dwordx4 v23, v[44:47], s[4:5]
	s_mov_b64 exec, -1
	v_cmp_le_i32_e32 vcc, -20, v50
	v_add_u32_e32 v22, 0x78280, v48
	s_mov_b64 exec, vcc
	global_store_dwordx4 v22, v[40:43], s[4:5]
	s_mov_b64 exec, -1
	v_cmp_ge_i32_e32 vcc, 11, v51
	v_add_u32_e32 v23, 0x78280, v49
	s_mov_b64 exec, vcc
	global_store_dwordx4 v23, v[44:47], s[4:5]
	s_mov_b64 exec, -1
	v_cmp_le_i32_e32 vcc, -22, v50
	v_add_u32_e32 v22, 0x842c0, v48
	s_mov_b64 exec, vcc
	global_store_dwordx4 v22, v[40:43], s[4:5]
	s_mov_b64 exec, -1
	v_cmp_ge_i32_e32 vcc, 9, v51
	v_add_u32_e32 v23, 0x842c0, v49
	s_mov_b64 exec, vcc
	global_store_dwordx4 v23, v[44:47], s[4:5]
	s_mov_b64 exec, -1
	v_cmp_le_i32_e32 vcc, -24, v50
	v_add_u32_e32 v22, 0x90300, v48
	s_mov_b64 exec, vcc
	global_store_dwordx4 v22, v[40:43], s[4:5]
	s_mov_b64 exec, -1
	v_cmp_ge_i32_e32 vcc, 7, v51
	v_add_u32_e32 v23, 0x90300, v49
	s_mov_b64 exec, vcc
	global_store_dwordx4 v23, v[44:47], s[4:5]
	s_mov_b64 exec, -1
	v_cmp_le_i32_e32 vcc, -26, v50
	v_add_u32_e32 v22, 0x9c340, v48
	s_mov_b64 exec, vcc
	global_store_dwordx4 v22, v[40:43], s[4:5]
	s_mov_b64 exec, -1
	v_cmp_ge_i32_e32 vcc, 5, v51
	v_add_u32_e32 v23, 0x9c340, v49
	s_mov_b64 exec, vcc
	global_store_dwordx4 v23, v[44:47], s[4:5]
	s_mov_b64 exec, -1
	v_cmp_le_i32_e32 vcc, -28, v50
	v_add_u32_e32 v22, 0xa8380, v48
	s_mov_b64 exec, vcc
	global_store_dwordx4 v22, v[40:43], s[4:5]
	s_mov_b64 exec, -1
	v_cmp_ge_i32_e32 vcc, 3, v51
	v_add_u32_e32 v23, 0xa8380, v49
	s_mov_b64 exec, vcc
	global_store_dwordx4 v23, v[44:47], s[4:5]
	s_mov_b64 exec, -1
	v_cmp_le_i32_e32 vcc, -30, v50
	v_add_u32_e32 v22, 0xb43c0, v48
	s_mov_b64 exec, vcc
	global_store_dwordx4 v22, v[40:43], s[4:5]
	s_mov_b64 exec, -1
	v_cmp_ge_i32_e32 vcc, 1, v51
	v_add_u32_e32 v23, 0xb43c0, v49
	s_mov_b64 exec, vcc
	global_store_dwordx4 v23, v[44:47], s[4:5]
	s_mov_b64 exec, -1
	s_branch .LBB0_106
